# v9 + residual L2 prefetch loads (1 dword per lane per K-iteration) in PA5/PB5 main loops
# baseline (speedup 1.0000x reference)
.LBB0_405:
	s_add_u32 s72, s70, 0xfff00080
	s_addc_u32 s73, s71, -1
	s_add_i32 s85, 0, 0x10000
	s_cmp_eq_u32 s84, 60
	s_cselect_b32 s75, s65, s73
	s_cselect_b32 s74, s80, s72
	v_add_u32_e32 v161, s85, v158
	s_cselect_b32 s73, s63, s83
	s_cselect_b32 s72, s81, s82
	s_add_i32 s88, 0, 0x14000
	ds_read_b128 v[154:157], v161
	ds_read_b128 v[170:173], v161 offset:1024
	ds_read_b128 v[174:177], v161 offset:2048
	ds_read_b128 v[178:181], v161 offset:3072
	v_add_u32_e32 v161, s88, v158
	ds_read_b128 v[182:185], v161
	ds_read_b128 v[186:189], v161 offset:1024
	ds_read_b128 v[194:197], v161 offset:2048
	ds_read_b128 v[198:201], v161 offset:3072
	v_mov_b32_e32 v240, s84
	v_lshl_add_u32 v241, s79, 8, v133
	v_lshl_or_b32 v242, s78, 8, v159
	v_bfe_u32 v243, v240, 2, 2
	v_lshl_add_u32 v241, v243, 4, v241
	v_bfe_u32 v243, v240, 4, 1
	v_lshl_add_u32 v241, v243, 7, v241
	v_lshl_add_u32 v241, v241, 11, v242
	v_bfe_u32 v243, v240, 1, 1
	v_lshl_add_u32 v241, v243, 7, v241
	v_lshlrev_b32_e32 v241, 1, v241
	global_load_dword v254, v241, s[54:55]
	v_lshl_add_u64 v[162:163], s[70:71], 0, v[150:151]
	s_add_i32 m0, s25, 0xc000
	ds_read_b128 v[202:205], v160
	ds_read_b128 v[206:209], v160 offset:1024
	ds_read_b128 v[210:213], v160 offset:2048
	ds_read_b128 v[214:217], v160 offset:3072
	ds_read_b128 v[218:221], v160 offset:4096
	ds_read_b128 v[222:225], v160 offset:5120
	ds_read_b128 v[226:229], v160 offset:6144
	ds_read_b128 v[230:233], v160 offset:7168
	global_load_lds_dwordx4 v[162:163], off
	v_lshl_add_u64 v[162:163], s[70:71], 0, v[152:153]
	s_add_i32 m0, s25, 0xe000
	s_nop 0
	global_load_lds_dwordx4 v[162:163], off
	s_waitcnt vmcnt(8)
	s_waitcnt lgkmcnt(0)
	s_barrier
	s_setprio 1
	s_waitcnt lgkmcnt(0)
	v_mfma_f32_16x16x32_bf16 v[128:131], v[154:157], v[202:205], v[128:131]
	v_mfma_f32_16x16x32_bf16 v[124:127], v[174:177], v[202:205], v[124:127]
	v_mfma_f32_16x16x32_bf16 v[112:115], v[154:157], v[210:213], v[112:115]
	v_mfma_f32_16x16x32_bf16 v[108:111], v[174:177], v[210:213], v[108:111]
	v_mfma_f32_16x16x32_bf16 v[96:99], v[154:157], v[218:221], v[96:99]
	v_mfma_f32_16x16x32_bf16 v[92:95], v[174:177], v[218:221], v[92:95]
	v_mfma_f32_16x16x32_bf16 v[80:83], v[154:157], v[226:229], v[80:83]
	v_mfma_f32_16x16x32_bf16 v[76:79], v[174:177], v[226:229], v[76:79]
	v_mfma_f32_16x16x32_bf16 v[128:131], v[170:173], v[206:209], v[128:131]
	v_mfma_f32_16x16x32_bf16 v[124:127], v[178:181], v[206:209], v[124:127]
	v_mfma_f32_16x16x32_bf16 v[112:115], v[170:173], v[214:217], v[112:115]
	v_mfma_f32_16x16x32_bf16 v[108:111], v[178:181], v[214:217], v[108:111]
	v_mfma_f32_16x16x32_bf16 v[96:99], v[170:173], v[222:225], v[96:99]
	v_mfma_f32_16x16x32_bf16 v[92:95], v[178:181], v[222:225], v[92:95]
	v_mfma_f32_16x16x32_bf16 v[80:83], v[170:173], v[230:233], v[80:83]
	v_mfma_f32_16x16x32_bf16 v[76:79], v[178:181], v[230:233], v[76:79]
	s_setprio 0
	s_setprio 1
	v_mfma_f32_16x16x32_bf16 v[120:123], v[182:185], v[202:205], v[120:123]
	v_mfma_f32_16x16x32_bf16 v[116:119], v[194:197], v[202:205], v[116:119]
	v_mfma_f32_16x16x32_bf16 v[104:107], v[182:185], v[210:213], v[104:107]
	v_mfma_f32_16x16x32_bf16 v[100:103], v[194:197], v[210:213], v[100:103]
	v_mfma_f32_16x16x32_bf16 v[88:91], v[182:185], v[218:221], v[88:91]
	v_mfma_f32_16x16x32_bf16 v[84:87], v[194:197], v[218:221], v[84:87]
	v_mfma_f32_16x16x32_bf16 v[72:75], v[182:185], v[226:229], v[72:75]
	v_mfma_f32_16x16x32_bf16 v[68:71], v[194:197], v[226:229], v[68:71]
	v_mfma_f32_16x16x32_bf16 v[120:123], v[186:189], v[206:209], v[120:123]
	v_mfma_f32_16x16x32_bf16 v[116:119], v[198:201], v[206:209], v[116:119]
	v_mfma_f32_16x16x32_bf16 v[104:107], v[186:189], v[214:217], v[104:107]
	v_mfma_f32_16x16x32_bf16 v[100:103], v[198:201], v[214:217], v[100:103]
	v_mfma_f32_16x16x32_bf16 v[88:91], v[186:189], v[222:225], v[88:91]
	v_mfma_f32_16x16x32_bf16 v[84:87], v[198:201], v[222:225], v[84:87]
	v_mfma_f32_16x16x32_bf16 v[72:75], v[186:189], v[230:233], v[72:75]
	v_mfma_f32_16x16x32_bf16 v[68:71], v[198:201], v[230:233], v[68:71]
	s_setprio 0
	s_barrier
	s_add_i32 s85, s85, s5
	v_lshl_add_u64 v[162:163], s[72:73], 0, v[146:147]
	s_mov_b32 m0, s85
	ds_read_b128 v[202:205], v160 offset:16384
	ds_read_b128 v[206:209], v160 offset:17408
	ds_read_b128 v[210:213], v160 offset:18432
	ds_read_b128 v[214:217], v160 offset:19456
	ds_read_b128 v[218:221], v160 offset:20480
	ds_read_b128 v[222:225], v160 offset:21504
	ds_read_b128 v[226:229], v160 offset:22528
	ds_read_b128 v[230:233], v160 offset:23552
	global_load_lds_dwordx4 v[162:163], off
	s_add_i32 m0, s85, 0x2000
	s_add_u32 s86, s72, 0x100000
	v_lshl_add_u64 v[190:191], s[72:73], 0, v[142:143]
	s_addc_u32 s87, s73, 0
	s_add_i32 s85, s88, s5
	global_load_lds_dwordx4 v[190:191], off
	v_lshl_add_u64 v[234:235], s[86:87], 0, v[146:147]
	s_mov_b32 m0, s85
	v_lshl_add_u64 v[236:237], s[74:75], 0, v[144:145]
	global_load_lds_dwordx4 v[234:235], off
	v_lshl_add_u64 v[234:235], s[86:87], 0, v[142:143]
	s_add_i32 m0, s85, 0x2000
	s_nop 0
	global_load_lds_dwordx4 v[234:235], off
	v_lshl_add_u64 v[234:235], s[74:75], 0, v[148:149]
	s_mov_b32 m0, s25
	s_nop 0
	global_load_lds_dwordx4 v[234:235], off
	s_mov_b32 m0, s33
	s_nop 0
	global_load_lds_dwordx4 v[236:237], off
	s_waitcnt vmcnt(8)
	s_waitcnt lgkmcnt(0)
	s_barrier
	s_setprio 1
	s_waitcnt lgkmcnt(0)
	v_mfma_f32_16x16x32_bf16 v[64:67], v[154:157], v[202:205], v[64:67]
	v_mfma_f32_16x16x32_bf16 v[60:63], v[174:177], v[202:205], v[60:63]
	v_mfma_f32_16x16x32_bf16 v[48:51], v[154:157], v[210:213], v[48:51]
	v_mfma_f32_16x16x32_bf16 v[44:47], v[174:177], v[210:213], v[44:47]
	v_mfma_f32_16x16x32_bf16 v[32:35], v[154:157], v[218:221], v[32:35]
	v_mfma_f32_16x16x32_bf16 v[28:31], v[174:177], v[218:221], v[28:31]
	v_mfma_f32_16x16x32_bf16 v[16:19], v[154:157], v[226:229], v[16:19]
	v_mfma_f32_16x16x32_bf16 v[12:15], v[174:177], v[226:229], v[12:15]
	v_mfma_f32_16x16x32_bf16 v[64:67], v[170:173], v[206:209], v[64:67]
	v_mfma_f32_16x16x32_bf16 v[60:63], v[178:181], v[206:209], v[60:63]
	v_mfma_f32_16x16x32_bf16 v[48:51], v[170:173], v[214:217], v[48:51]
	v_mfma_f32_16x16x32_bf16 v[44:47], v[178:181], v[214:217], v[44:47]
	v_mfma_f32_16x16x32_bf16 v[32:35], v[170:173], v[222:225], v[32:35]
	v_mfma_f32_16x16x32_bf16 v[28:31], v[178:181], v[222:225], v[28:31]
	v_mfma_f32_16x16x32_bf16 v[16:19], v[170:173], v[230:233], v[16:19]
	v_mfma_f32_16x16x32_bf16 v[12:15], v[178:181], v[230:233], v[12:15]
	s_setprio 0
	s_setprio 1
	v_mfma_f32_16x16x32_bf16 v[56:59], v[182:185], v[202:205], v[56:59]
	v_mfma_f32_16x16x32_bf16 v[52:55], v[194:197], v[202:205], v[52:55]
	v_mfma_f32_16x16x32_bf16 v[40:43], v[182:185], v[210:213], v[40:43]
	v_mfma_f32_16x16x32_bf16 v[36:39], v[194:197], v[210:213], v[36:39]
	v_mfma_f32_16x16x32_bf16 v[24:27], v[182:185], v[218:221], v[24:27]
	v_mfma_f32_16x16x32_bf16 v[20:23], v[194:197], v[218:221], v[20:23]
	v_mfma_f32_16x16x32_bf16 v[8:11], v[182:185], v[226:229], v[8:11]
	v_mfma_f32_16x16x32_bf16 v[4:7], v[194:197], v[226:229], v[4:7]
	v_mfma_f32_16x16x32_bf16 v[56:59], v[186:189], v[206:209], v[56:59]
	v_mfma_f32_16x16x32_bf16 v[52:55], v[198:201], v[206:209], v[52:55]
	v_mfma_f32_16x16x32_bf16 v[40:43], v[186:189], v[214:217], v[40:43]
	v_mfma_f32_16x16x32_bf16 v[36:39], v[198:201], v[214:217], v[36:39]
	v_mfma_f32_16x16x32_bf16 v[24:27], v[186:189], v[222:225], v[24:27]
	v_mfma_f32_16x16x32_bf16 v[20:23], v[198:201], v[222:225], v[20:23]
	v_mfma_f32_16x16x32_bf16 v[8:11], v[186:189], v[230:233], v[8:11]
	v_mfma_f32_16x16x32_bf16 v[4:7], v[198:201], v[230:233], v[4:7]
	s_setprio 0
	s_barrier
	s_add_i32 s85, 0, 0x18000
	v_add_u32_e32 v161, s85, v158
	s_add_i32 s86, 0, 0x1c000
	ds_read_b128 v[154:157], v161
	ds_read_b128 v[170:173], v161 offset:1024
	ds_read_b128 v[174:177], v161 offset:2048
	ds_read_b128 v[178:181], v161 offset:3072
	v_add_u32_e32 v161, s86, v158
	ds_read_b128 v[182:185], v161
	ds_read_b128 v[186:189], v161 offset:1024
	ds_read_b128 v[194:197], v161 offset:2048
	ds_read_b128 v[198:201], v161 offset:3072
	s_add_u32 s74, s74, 0x100000
	s_addc_u32 s75, s75, 0
	s_mov_b32 m0, s34
	v_lshl_add_u64 v[238:239], s[74:75], 0, v[148:149]
	ds_read_b128 v[202:205], v160 offset:32768
	ds_read_b128 v[206:209], v160 offset:33792
	ds_read_b128 v[210:213], v160 offset:34816
	ds_read_b128 v[214:217], v160 offset:35840
	ds_read_b128 v[218:221], v160 offset:36864
	ds_read_b128 v[222:225], v160 offset:37888
	ds_read_b128 v[226:229], v160 offset:38912
	ds_read_b128 v[230:233], v160 offset:39936
	global_load_lds_dwordx4 v[238:239], off
	v_lshl_add_u64 v[238:239], s[74:75], 0, v[144:145]
	s_mov_b32 m0, s76
	s_nop 0
	global_load_lds_dwordx4 v[238:239], off
	s_waitcnt vmcnt(8)
	s_waitcnt lgkmcnt(0)
	s_barrier
	s_setprio 1
	s_waitcnt lgkmcnt(0)
	v_mfma_f32_16x16x32_bf16 v[128:131], v[154:157], v[202:205], v[128:131]
	v_mfma_f32_16x16x32_bf16 v[124:127], v[174:177], v[202:205], v[124:127]
	v_mfma_f32_16x16x32_bf16 v[112:115], v[154:157], v[210:213], v[112:115]
	v_mfma_f32_16x16x32_bf16 v[108:111], v[174:177], v[210:213], v[108:111]
	v_mfma_f32_16x16x32_bf16 v[96:99], v[154:157], v[218:221], v[96:99]
	v_mfma_f32_16x16x32_bf16 v[92:95], v[174:177], v[218:221], v[92:95]
	v_mfma_f32_16x16x32_bf16 v[80:83], v[154:157], v[226:229], v[80:83]
	v_mfma_f32_16x16x32_bf16 v[76:79], v[174:177], v[226:229], v[76:79]
	v_mfma_f32_16x16x32_bf16 v[128:131], v[170:173], v[206:209], v[128:131]
	v_mfma_f32_16x16x32_bf16 v[124:127], v[178:181], v[206:209], v[124:127]
	v_mfma_f32_16x16x32_bf16 v[112:115], v[170:173], v[214:217], v[112:115]
	v_mfma_f32_16x16x32_bf16 v[108:111], v[178:181], v[214:217], v[108:111]
	v_mfma_f32_16x16x32_bf16 v[96:99], v[170:173], v[222:225], v[96:99]
	v_mfma_f32_16x16x32_bf16 v[92:95], v[178:181], v[222:225], v[92:95]
	v_mfma_f32_16x16x32_bf16 v[80:83], v[170:173], v[230:233], v[80:83]
	v_mfma_f32_16x16x32_bf16 v[76:79], v[178:181], v[230:233], v[76:79]
	s_setprio 0
	s_setprio 1
	v_mfma_f32_16x16x32_bf16 v[120:123], v[182:185], v[202:205], v[120:123]
	v_mfma_f32_16x16x32_bf16 v[116:119], v[194:197], v[202:205], v[116:119]
	v_mfma_f32_16x16x32_bf16 v[104:107], v[182:185], v[210:213], v[104:107]
	v_mfma_f32_16x16x32_bf16 v[100:103], v[194:197], v[210:213], v[100:103]
	v_mfma_f32_16x16x32_bf16 v[88:91], v[182:185], v[218:221], v[88:91]
	v_mfma_f32_16x16x32_bf16 v[84:87], v[194:197], v[218:221], v[84:87]
	v_mfma_f32_16x16x32_bf16 v[72:75], v[182:185], v[226:229], v[72:75]
	v_mfma_f32_16x16x32_bf16 v[68:71], v[194:197], v[226:229], v[68:71]
	v_mfma_f32_16x16x32_bf16 v[120:123], v[186:189], v[206:209], v[120:123]
	v_mfma_f32_16x16x32_bf16 v[116:119], v[198:201], v[206:209], v[116:119]
	v_mfma_f32_16x16x32_bf16 v[104:107], v[186:189], v[214:217], v[104:107]
	v_mfma_f32_16x16x32_bf16 v[100:103], v[198:201], v[214:217], v[100:103]
	v_mfma_f32_16x16x32_bf16 v[88:91], v[186:189], v[222:225], v[88:91]
	v_mfma_f32_16x16x32_bf16 v[84:87], v[198:201], v[222:225], v[84:87]
	v_mfma_f32_16x16x32_bf16 v[72:75], v[186:189], v[230:233], v[72:75]
	v_mfma_f32_16x16x32_bf16 v[68:71], v[198:201], v[230:233], v[68:71]
	s_setprio 0
	s_barrier
	s_add_i32 s74, s85, s5
	v_lshl_add_u64 v[162:163], v[162:163], 0, s[50:51]
	s_mov_b32 m0, s74
	ds_read_b128 v[202:205], v160 offset:49152
	ds_read_b128 v[206:209], v160 offset:50176
	ds_read_b128 v[210:213], v160 offset:51200
	ds_read_b128 v[214:217], v160 offset:52224
	ds_read_b128 v[218:221], v160 offset:53248
	ds_read_b128 v[222:225], v160 offset:54272
	ds_read_b128 v[226:229], v160 offset:55296
	ds_read_b128 v[230:233], v160 offset:56320
	global_load_lds_dwordx4 v[162:163], off
	s_add_i32 m0, s74, 0x2000
	s_add_u32 s72, s72, 0x100080
	v_lshl_add_u64 v[162:163], v[190:191], 0, s[50:51]
	s_addc_u32 s73, s73, 0
	s_add_i32 s74, s86, s5
	global_load_lds_dwordx4 v[162:163], off
	v_lshl_add_u64 v[162:163], s[72:73], 0, v[146:147]
	s_mov_b32 m0, s74
	s_nop 0
	global_load_lds_dwordx4 v[162:163], off
	v_lshl_add_u64 v[162:163], s[72:73], 0, v[142:143]
	s_add_i32 m0, s74, 0x2000
	s_nop 0
	global_load_lds_dwordx4 v[162:163], off
	v_lshl_add_u64 v[162:163], v[234:235], 0, s[50:51]
	s_mov_b32 m0, s24
	s_nop 0
	global_load_lds_dwordx4 v[162:163], off
	v_lshl_add_u64 v[162:163], v[236:237], 0, s[50:51]
	s_mov_b32 m0, s30
	s_nop 0
	global_load_lds_dwordx4 v[162:163], off
	s_waitcnt vmcnt(8)
	s_waitcnt lgkmcnt(0)
	s_barrier
	s_setprio 1
	s_waitcnt lgkmcnt(0)
	v_mfma_f32_16x16x32_bf16 v[64:67], v[154:157], v[202:205], v[64:67]
	v_mfma_f32_16x16x32_bf16 v[60:63], v[174:177], v[202:205], v[60:63]
	v_mfma_f32_16x16x32_bf16 v[48:51], v[154:157], v[210:213], v[48:51]
	v_mfma_f32_16x16x32_bf16 v[44:47], v[174:177], v[210:213], v[44:47]
	v_mfma_f32_16x16x32_bf16 v[32:35], v[154:157], v[218:221], v[32:35]
	v_mfma_f32_16x16x32_bf16 v[28:31], v[174:177], v[218:221], v[28:31]
	v_mfma_f32_16x16x32_bf16 v[16:19], v[154:157], v[226:229], v[16:19]
	v_mfma_f32_16x16x32_bf16 v[12:15], v[174:177], v[226:229], v[12:15]
	v_mfma_f32_16x16x32_bf16 v[64:67], v[170:173], v[206:209], v[64:67]
	v_mfma_f32_16x16x32_bf16 v[60:63], v[178:181], v[206:209], v[60:63]
	v_mfma_f32_16x16x32_bf16 v[48:51], v[170:173], v[214:217], v[48:51]
	v_mfma_f32_16x16x32_bf16 v[44:47], v[178:181], v[214:217], v[44:47]
	v_mfma_f32_16x16x32_bf16 v[32:35], v[170:173], v[222:225], v[32:35]
	v_mfma_f32_16x16x32_bf16 v[28:31], v[178:181], v[222:225], v[28:31]
	v_mfma_f32_16x16x32_bf16 v[16:19], v[170:173], v[230:233], v[16:19]
	v_mfma_f32_16x16x32_bf16 v[12:15], v[178:181], v[230:233], v[12:15]
	s_setprio 0
	s_setprio 1
	v_mfma_f32_16x16x32_bf16 v[56:59], v[182:185], v[202:205], v[56:59]
	v_mfma_f32_16x16x32_bf16 v[52:55], v[194:197], v[202:205], v[52:55]
	v_mfma_f32_16x16x32_bf16 v[40:43], v[182:185], v[210:213], v[40:43]
	v_mfma_f32_16x16x32_bf16 v[36:39], v[194:197], v[210:213], v[36:39]
	v_mfma_f32_16x16x32_bf16 v[24:27], v[182:185], v[218:221], v[24:27]
	v_mfma_f32_16x16x32_bf16 v[20:23], v[194:197], v[218:221], v[20:23]
	v_mfma_f32_16x16x32_bf16 v[8:11], v[182:185], v[226:229], v[8:11]
	v_mfma_f32_16x16x32_bf16 v[4:7], v[194:197], v[226:229], v[4:7]
	v_mfma_f32_16x16x32_bf16 v[56:59], v[186:189], v[206:209], v[56:59]
	v_mfma_f32_16x16x32_bf16 v[52:55], v[198:201], v[206:209], v[52:55]
	v_mfma_f32_16x16x32_bf16 v[40:43], v[186:189], v[214:217], v[40:43]
	v_mfma_f32_16x16x32_bf16 v[36:39], v[198:201], v[214:217], v[36:39]
	v_mfma_f32_16x16x32_bf16 v[24:27], v[186:189], v[222:225], v[24:27]
	v_mfma_f32_16x16x32_bf16 v[20:23], v[198:201], v[222:225], v[20:23]
	v_mfma_f32_16x16x32_bf16 v[8:11], v[186:189], v[230:233], v[8:11]
	v_mfma_f32_16x16x32_bf16 v[4:7], v[198:201], v[230:233], v[4:7]
	s_setprio 0
	s_barrier
	s_add_i32 s84, s84, 2
	s_add_u32 s70, s70, 0x100
	s_addc_u32 s71, s71, 0
	s_add_u32 s82, s82, 0x100
	s_addc_u32 s83, s83, 0
	s_cmp_gt_u32 s84, 61
	s_cbranch_scc0 .LBB0_405
	s_and_b64 vcc, exec, s[60:61]
	s_cbranch_vccz .LBB0_408
	s_barrier

.LBB0_855:
	s_add_u32 s63, s12, 0xfff80080
	s_addc_u32 s74, s13, -1
	s_add_i32 s75, 0, 0x10000
	s_cmp_eq_u32 s62, 28
	s_cselect_b32 s79, s45, s74
	s_cselect_b32 s78, s51, s63
	v_add_u32_e32 v146, s75, v149
	s_cselect_b32 s77, s31, s60
	s_cselect_b32 s76, s52, s56
	s_add_i32 s63, 0, 0x14000
	ds_read_b128 v[138:141], v146
	ds_read_b128 v[142:145], v146 offset:1024
	ds_read_b128 v[152:155], v146 offset:2048
	ds_read_b128 v[156:159], v146 offset:3072
	v_add_u32_e32 v146, s63, v149
	ds_read_b128 v[160:163], v146
	ds_read_b128 v[164:167], v146 offset:1024
	ds_read_b128 v[168:171], v146 offset:2048
	ds_read_b128 v[172:175], v146 offset:3072
	v_mov_b32_e32 v240, s62
	v_lshl_add_u32 v241, s49, 8, v148
	v_lshl_or_b32 v242, s4, 8, v150
	v_bfe_u32 v243, v240, 2, 2
	v_lshl_add_u32 v241, v243, 4, v241
	v_bfe_u32 v243, v240, 4, 1
	v_lshl_add_u32 v241, v243, 7, v241
	v_lshl_add_u32 v241, v241, 11, v242
	v_bfe_u32 v243, v240, 1, 1
	v_lshl_add_u32 v241, v243, 7, v241
	v_lshlrev_b32_e32 v241, 1, v241
	global_load_dword v254, v241, s[16:17]
	v_lshl_add_u64 v[146:147], s[12:13], 0, v[134:135]
	s_add_i32 m0, s40, 0xc000
	ds_read_b128 v[180:183], v151
	ds_read_b128 v[184:187], v151 offset:1024
	ds_read_b128 v[188:191], v151 offset:2048
	ds_read_b128 v[200:203], v151 offset:3072
	ds_read_b128 v[204:207], v151 offset:4096
	ds_read_b128 v[208:211], v151 offset:5120
	ds_read_b128 v[212:215], v151 offset:6144
	ds_read_b128 v[216:219], v151 offset:7168
	global_load_lds_dwordx4 v[146:147], off
	v_lshl_add_u64 v[146:147], s[12:13], 0, v[136:137]
	s_add_i32 m0, s40, 0xe000
	s_nop 0
	global_load_lds_dwordx4 v[146:147], off
	s_waitcnt vmcnt(8)
	s_waitcnt lgkmcnt(0)
	s_barrier
	s_setprio 1
	s_waitcnt lgkmcnt(0)
	v_mfma_f32_16x16x32_bf16 v[124:127], v[138:141], v[180:183], v[124:127]
	v_mfma_f32_16x16x32_bf16 v[120:123], v[152:155], v[180:183], v[120:123]
	v_mfma_f32_16x16x32_bf16 v[108:111], v[138:141], v[188:191], v[108:111]
	v_mfma_f32_16x16x32_bf16 v[104:107], v[152:155], v[188:191], v[104:107]
	v_mfma_f32_16x16x32_bf16 v[92:95], v[138:141], v[204:207], v[92:95]
	v_mfma_f32_16x16x32_bf16 v[88:91], v[152:155], v[204:207], v[88:91]
	v_mfma_f32_16x16x32_bf16 v[76:79], v[138:141], v[212:215], v[76:79]
	v_mfma_f32_16x16x32_bf16 v[72:75], v[152:155], v[212:215], v[72:75]
	v_mfma_f32_16x16x32_bf16 v[124:127], v[142:145], v[184:187], v[124:127]
	v_mfma_f32_16x16x32_bf16 v[120:123], v[156:159], v[184:187], v[120:123]
	v_mfma_f32_16x16x32_bf16 v[108:111], v[142:145], v[200:203], v[108:111]
	v_mfma_f32_16x16x32_bf16 v[104:107], v[156:159], v[200:203], v[104:107]
	v_mfma_f32_16x16x32_bf16 v[92:95], v[142:145], v[208:211], v[92:95]
	v_mfma_f32_16x16x32_bf16 v[88:91], v[156:159], v[208:211], v[88:91]
	v_mfma_f32_16x16x32_bf16 v[76:79], v[142:145], v[216:219], v[76:79]
	v_mfma_f32_16x16x32_bf16 v[72:75], v[156:159], v[216:219], v[72:75]
	s_setprio 0
	s_setprio 1
	v_mfma_f32_16x16x32_bf16 v[116:119], v[160:163], v[180:183], v[116:119]
	v_mfma_f32_16x16x32_bf16 v[112:115], v[168:171], v[180:183], v[112:115]
	v_mfma_f32_16x16x32_bf16 v[100:103], v[160:163], v[188:191], v[100:103]
	v_mfma_f32_16x16x32_bf16 v[96:99], v[168:171], v[188:191], v[96:99]
	v_mfma_f32_16x16x32_bf16 v[84:87], v[160:163], v[204:207], v[84:87]
	v_mfma_f32_16x16x32_bf16 v[80:83], v[168:171], v[204:207], v[80:83]
	v_mfma_f32_16x16x32_bf16 v[68:71], v[160:163], v[212:215], v[68:71]
	v_mfma_f32_16x16x32_bf16 v[64:67], v[168:171], v[212:215], v[64:67]
	v_mfma_f32_16x16x32_bf16 v[116:119], v[164:167], v[184:187], v[116:119]
	v_mfma_f32_16x16x32_bf16 v[112:115], v[172:175], v[184:187], v[112:115]
	v_mfma_f32_16x16x32_bf16 v[100:103], v[164:167], v[200:203], v[100:103]
	v_mfma_f32_16x16x32_bf16 v[96:99], v[172:175], v[200:203], v[96:99]
	v_mfma_f32_16x16x32_bf16 v[84:87], v[164:167], v[208:211], v[84:87]
	v_mfma_f32_16x16x32_bf16 v[80:83], v[172:175], v[208:211], v[80:83]
	v_mfma_f32_16x16x32_bf16 v[68:71], v[164:167], v[216:219], v[68:71]
	v_mfma_f32_16x16x32_bf16 v[64:67], v[172:175], v[216:219], v[64:67]
	s_setprio 0
	s_barrier
	s_add_i32 s74, s75, s2
	v_lshl_add_u64 v[146:147], s[76:77], 0, v[176:177]
	s_mov_b32 m0, s74
	ds_read_b128 v[180:183], v151 offset:16384
	ds_read_b128 v[184:187], v151 offset:17408
	ds_read_b128 v[188:191], v151 offset:18432
	ds_read_b128 v[200:203], v151 offset:19456
	ds_read_b128 v[204:207], v151 offset:20480
	ds_read_b128 v[208:211], v151 offset:21504
	ds_read_b128 v[212:215], v151 offset:22528
	ds_read_b128 v[216:219], v151 offset:23552
	global_load_lds_dwordx4 v[146:147], off
	s_add_i32 m0, s74, 0x2000
	s_add_u32 s74, s76, 0x80000
	v_lshl_add_u64 v[194:195], s[76:77], 0, v[128:129]
	s_addc_u32 s75, s77, 0
	s_add_i32 s63, s63, s2
	global_load_lds_dwordx4 v[194:195], off
	v_lshl_add_u64 v[220:221], s[74:75], 0, v[176:177]
	s_mov_b32 m0, s63
	v_lshl_add_u64 v[222:223], s[78:79], 0, v[130:131]
	global_load_lds_dwordx4 v[220:221], off
	v_lshl_add_u64 v[220:221], s[74:75], 0, v[128:129]
	s_add_i32 m0, s63, 0x2000
	s_nop 0
	global_load_lds_dwordx4 v[220:221], off
	v_lshl_add_u64 v[220:221], s[78:79], 0, v[132:133]
	s_mov_b32 m0, s40
	s_nop 0
	global_load_lds_dwordx4 v[220:221], off
	s_mov_b32 m0, s41
	s_nop 0
	global_load_lds_dwordx4 v[222:223], off
	s_waitcnt vmcnt(8)
	s_waitcnt lgkmcnt(0)
	s_barrier
	s_setprio 1
	s_waitcnt lgkmcnt(0)
	v_mfma_f32_16x16x32_bf16 v[60:63], v[138:141], v[180:183], v[60:63]
	v_mfma_f32_16x16x32_bf16 v[56:59], v[152:155], v[180:183], v[56:59]
	v_mfma_f32_16x16x32_bf16 v[44:47], v[138:141], v[188:191], v[44:47]
	v_mfma_f32_16x16x32_bf16 v[40:43], v[152:155], v[188:191], v[40:43]
	v_mfma_f32_16x16x32_bf16 v[28:31], v[138:141], v[204:207], v[28:31]
	v_mfma_f32_16x16x32_bf16 v[24:27], v[152:155], v[204:207], v[24:27]
	v_mfma_f32_16x16x32_bf16 v[12:15], v[138:141], v[212:215], v[12:15]
	v_mfma_f32_16x16x32_bf16 v[8:11], v[152:155], v[212:215], v[8:11]
	v_mfma_f32_16x16x32_bf16 v[60:63], v[142:145], v[184:187], v[60:63]
	v_mfma_f32_16x16x32_bf16 v[56:59], v[156:159], v[184:187], v[56:59]
	v_mfma_f32_16x16x32_bf16 v[44:47], v[142:145], v[200:203], v[44:47]
	v_mfma_f32_16x16x32_bf16 v[40:43], v[156:159], v[200:203], v[40:43]
	v_mfma_f32_16x16x32_bf16 v[28:31], v[142:145], v[208:211], v[28:31]
	v_mfma_f32_16x16x32_bf16 v[24:27], v[156:159], v[208:211], v[24:27]
	v_mfma_f32_16x16x32_bf16 v[12:15], v[142:145], v[216:219], v[12:15]
	v_mfma_f32_16x16x32_bf16 v[8:11], v[156:159], v[216:219], v[8:11]
	s_setprio 0
	s_setprio 1
	v_mfma_f32_16x16x32_bf16 v[52:55], v[160:163], v[180:183], v[52:55]
	v_mfma_f32_16x16x32_bf16 v[48:51], v[168:171], v[180:183], v[48:51]
	v_mfma_f32_16x16x32_bf16 v[36:39], v[160:163], v[188:191], v[36:39]
	v_mfma_f32_16x16x32_bf16 v[32:35], v[168:171], v[188:191], v[32:35]
	v_mfma_f32_16x16x32_bf16 v[20:23], v[160:163], v[204:207], v[20:23]
	v_mfma_f32_16x16x32_bf16 v[16:19], v[168:171], v[204:207], v[16:19]
	v_mfma_f32_16x16x32_bf16 v[4:7], v[160:163], v[212:215], v[4:7]
	v_mfma_f32_16x16x32_bf16 v[0:3], v[168:171], v[212:215], v[0:3]
	v_mfma_f32_16x16x32_bf16 v[52:55], v[164:167], v[184:187], v[52:55]
	v_mfma_f32_16x16x32_bf16 v[48:51], v[172:175], v[184:187], v[48:51]
	v_mfma_f32_16x16x32_bf16 v[36:39], v[164:167], v[200:203], v[36:39]
	v_mfma_f32_16x16x32_bf16 v[32:35], v[172:175], v[200:203], v[32:35]
	v_mfma_f32_16x16x32_bf16 v[20:23], v[164:167], v[208:211], v[20:23]
	v_mfma_f32_16x16x32_bf16 v[16:19], v[172:175], v[208:211], v[16:19]
	v_mfma_f32_16x16x32_bf16 v[4:7], v[164:167], v[216:219], v[4:7]
	v_mfma_f32_16x16x32_bf16 v[0:3], v[172:175], v[216:219], v[0:3]
	s_setprio 0
	s_barrier
	s_add_i32 s63, 0, 0x18000
	s_add_i32 s80, 0, 0x1c000
	v_add_u32_e32 v156, s63, v149
	v_add_u32_e32 v172, s80, v149
	ds_read_b128 v[138:141], v156
	ds_read_b128 v[142:145], v156 offset:1024
	ds_read_b128 v[152:155], v156 offset:2048
	ds_read_b128 v[156:159], v156 offset:3072
	ds_read_b128 v[160:163], v172
	ds_read_b128 v[164:167], v172 offset:1024
	ds_read_b128 v[168:171], v172 offset:2048
	ds_read_b128 v[172:175], v172 offset:3072
	s_add_u32 s74, s78, 0x80000
	s_addc_u32 s75, s79, 0
	s_mov_b32 m0, s42
	v_lshl_add_u64 v[224:225], s[74:75], 0, v[132:133]
	ds_read_b128 v[180:183], v151 offset:32768
	ds_read_b128 v[184:187], v151 offset:33792
	ds_read_b128 v[188:191], v151 offset:34816
	ds_read_b128 v[200:203], v151 offset:35840
	ds_read_b128 v[204:207], v151 offset:36864
	ds_read_b128 v[208:211], v151 offset:37888
	ds_read_b128 v[212:215], v151 offset:38912
	ds_read_b128 v[216:219], v151 offset:39936
	global_load_lds_dwordx4 v[224:225], off
	v_lshl_add_u64 v[224:225], s[74:75], 0, v[130:131]
	s_mov_b32 m0, s48
	s_nop 0
	global_load_lds_dwordx4 v[224:225], off
	s_waitcnt vmcnt(8)
	s_waitcnt lgkmcnt(0)
	s_barrier
	s_setprio 1
	s_waitcnt lgkmcnt(0)
	v_mfma_f32_16x16x32_bf16 v[124:127], v[138:141], v[180:183], v[124:127]
	v_mfma_f32_16x16x32_bf16 v[120:123], v[152:155], v[180:183], v[120:123]
	v_mfma_f32_16x16x32_bf16 v[108:111], v[138:141], v[188:191], v[108:111]
	v_mfma_f32_16x16x32_bf16 v[104:107], v[152:155], v[188:191], v[104:107]
	v_mfma_f32_16x16x32_bf16 v[92:95], v[138:141], v[204:207], v[92:95]
	v_mfma_f32_16x16x32_bf16 v[88:91], v[152:155], v[204:207], v[88:91]
	v_mfma_f32_16x16x32_bf16 v[76:79], v[138:141], v[212:215], v[76:79]
	v_mfma_f32_16x16x32_bf16 v[72:75], v[152:155], v[212:215], v[72:75]
	v_mfma_f32_16x16x32_bf16 v[124:127], v[142:145], v[184:187], v[124:127]
	v_mfma_f32_16x16x32_bf16 v[120:123], v[156:159], v[184:187], v[120:123]
	v_mfma_f32_16x16x32_bf16 v[108:111], v[142:145], v[200:203], v[108:111]
	v_mfma_f32_16x16x32_bf16 v[104:107], v[156:159], v[200:203], v[104:107]
	v_mfma_f32_16x16x32_bf16 v[92:95], v[142:145], v[208:211], v[92:95]
	v_mfma_f32_16x16x32_bf16 v[88:91], v[156:159], v[208:211], v[88:91]
	v_mfma_f32_16x16x32_bf16 v[76:79], v[142:145], v[216:219], v[76:79]
	v_mfma_f32_16x16x32_bf16 v[72:75], v[156:159], v[216:219], v[72:75]
	s_setprio 0
	s_setprio 1
	v_mfma_f32_16x16x32_bf16 v[116:119], v[160:163], v[180:183], v[116:119]
	v_mfma_f32_16x16x32_bf16 v[112:115], v[168:171], v[180:183], v[112:115]
	v_mfma_f32_16x16x32_bf16 v[100:103], v[160:163], v[188:191], v[100:103]
	v_mfma_f32_16x16x32_bf16 v[96:99], v[168:171], v[188:191], v[96:99]
	v_mfma_f32_16x16x32_bf16 v[84:87], v[160:163], v[204:207], v[84:87]
	v_mfma_f32_16x16x32_bf16 v[80:83], v[168:171], v[204:207], v[80:83]
	v_mfma_f32_16x16x32_bf16 v[68:71], v[160:163], v[212:215], v[68:71]
	v_mfma_f32_16x16x32_bf16 v[64:67], v[168:171], v[212:215], v[64:67]
	v_mfma_f32_16x16x32_bf16 v[116:119], v[164:167], v[184:187], v[116:119]
	v_mfma_f32_16x16x32_bf16 v[112:115], v[172:175], v[184:187], v[112:115]
	v_mfma_f32_16x16x32_bf16 v[100:103], v[164:167], v[200:203], v[100:103]
	v_mfma_f32_16x16x32_bf16 v[96:99], v[172:175], v[200:203], v[96:99]
	v_mfma_f32_16x16x32_bf16 v[84:87], v[164:167], v[208:211], v[84:87]
	v_mfma_f32_16x16x32_bf16 v[80:83], v[172:175], v[208:211], v[80:83]
	v_mfma_f32_16x16x32_bf16 v[68:71], v[164:167], v[216:219], v[68:71]
	v_mfma_f32_16x16x32_bf16 v[64:67], v[172:175], v[216:219], v[64:67]
	s_setprio 0
	s_barrier
	s_add_i32 s63, s63, s2
	v_lshl_add_u64 v[146:147], v[146:147], 0, s[64:65]
	s_mov_b32 m0, s63
	ds_read_b128 v[180:183], v151 offset:49152
	ds_read_b128 v[184:187], v151 offset:50176
	ds_read_b128 v[188:191], v151 offset:51200
	ds_read_b128 v[200:203], v151 offset:52224
	ds_read_b128 v[204:207], v151 offset:53248
	ds_read_b128 v[208:211], v151 offset:54272
	ds_read_b128 v[212:215], v151 offset:55296
	ds_read_b128 v[216:219], v151 offset:56320
	global_load_lds_dwordx4 v[146:147], off
	s_add_i32 m0, s63, 0x2000
	s_add_u32 s74, s76, 0x80080
	v_lshl_add_u64 v[146:147], v[194:195], 0, s[64:65]
	s_addc_u32 s75, s77, 0
	s_add_i32 s63, s80, s2
	global_load_lds_dwordx4 v[146:147], off
	v_lshl_add_u64 v[146:147], s[74:75], 0, v[176:177]
	s_mov_b32 m0, s63
	s_nop 0
	global_load_lds_dwordx4 v[146:147], off
	v_lshl_add_u64 v[146:147], s[74:75], 0, v[128:129]
	s_add_i32 m0, s63, 0x2000
	s_nop 0
	global_load_lds_dwordx4 v[146:147], off
	v_lshl_add_u64 v[146:147], v[220:221], 0, s[64:65]
	s_mov_b32 m0, s55
	s_nop 0
	global_load_lds_dwordx4 v[146:147], off
	v_lshl_add_u64 v[146:147], v[222:223], 0, s[64:65]
	s_mov_b32 m0, s58
	s_nop 0
	global_load_lds_dwordx4 v[146:147], off
	s_waitcnt vmcnt(8)
	s_waitcnt lgkmcnt(0)
	s_barrier
	s_setprio 1
	s_waitcnt lgkmcnt(0)
	v_mfma_f32_16x16x32_bf16 v[60:63], v[138:141], v[180:183], v[60:63]
	v_mfma_f32_16x16x32_bf16 v[56:59], v[152:155], v[180:183], v[56:59]
	v_mfma_f32_16x16x32_bf16 v[44:47], v[138:141], v[188:191], v[44:47]
	v_mfma_f32_16x16x32_bf16 v[40:43], v[152:155], v[188:191], v[40:43]
	v_mfma_f32_16x16x32_bf16 v[28:31], v[138:141], v[204:207], v[28:31]
	v_mfma_f32_16x16x32_bf16 v[24:27], v[152:155], v[204:207], v[24:27]
	v_mfma_f32_16x16x32_bf16 v[12:15], v[138:141], v[212:215], v[12:15]
	v_mfma_f32_16x16x32_bf16 v[8:11], v[152:155], v[212:215], v[8:11]
	v_mfma_f32_16x16x32_bf16 v[60:63], v[142:145], v[184:187], v[60:63]
	v_mfma_f32_16x16x32_bf16 v[56:59], v[156:159], v[184:187], v[56:59]
	v_mfma_f32_16x16x32_bf16 v[44:47], v[142:145], v[200:203], v[44:47]
	v_mfma_f32_16x16x32_bf16 v[40:43], v[156:159], v[200:203], v[40:43]
	v_mfma_f32_16x16x32_bf16 v[28:31], v[142:145], v[208:211], v[28:31]
	v_mfma_f32_16x16x32_bf16 v[24:27], v[156:159], v[208:211], v[24:27]
	v_mfma_f32_16x16x32_bf16 v[12:15], v[142:145], v[216:219], v[12:15]
	v_mfma_f32_16x16x32_bf16 v[8:11], v[156:159], v[216:219], v[8:11]
	s_setprio 0
	s_setprio 1
	v_mfma_f32_16x16x32_bf16 v[52:55], v[160:163], v[180:183], v[52:55]
	v_mfma_f32_16x16x32_bf16 v[48:51], v[168:171], v[180:183], v[48:51]
	v_mfma_f32_16x16x32_bf16 v[36:39], v[160:163], v[188:191], v[36:39]
	v_mfma_f32_16x16x32_bf16 v[32:35], v[168:171], v[188:191], v[32:35]
	v_mfma_f32_16x16x32_bf16 v[20:23], v[160:163], v[204:207], v[20:23]
	v_mfma_f32_16x16x32_bf16 v[16:19], v[168:171], v[204:207], v[16:19]
	v_mfma_f32_16x16x32_bf16 v[4:7], v[160:163], v[212:215], v[4:7]
	v_mfma_f32_16x16x32_bf16 v[0:3], v[168:171], v[212:215], v[0:3]
	v_mfma_f32_16x16x32_bf16 v[52:55], v[164:167], v[184:187], v[52:55]
	v_mfma_f32_16x16x32_bf16 v[48:51], v[172:175], v[184:187], v[48:51]
	v_mfma_f32_16x16x32_bf16 v[36:39], v[164:167], v[200:203], v[36:39]
	v_mfma_f32_16x16x32_bf16 v[32:35], v[172:175], v[200:203], v[32:35]
	v_mfma_f32_16x16x32_bf16 v[20:23], v[164:167], v[208:211], v[20:23]
	v_mfma_f32_16x16x32_bf16 v[16:19], v[172:175], v[208:211], v[16:19]
	v_mfma_f32_16x16x32_bf16 v[4:7], v[164:167], v[216:219], v[4:7]
	v_mfma_f32_16x16x32_bf16 v[0:3], v[172:175], v[216:219], v[0:3]
	s_setprio 0
	s_barrier
	s_add_i32 s62, s62, 2
	s_add_u32 s12, s12, 0x100
	s_addc_u32 s13, s13, 0
	s_add_u32 s56, s56, 0x100
	s_addc_u32 s60, s60, 0
	s_cmp_gt_u32 s62, 29
	s_cbranch_scc0 .LBB0_855
	s_and_b64 vcc, exec, s[26:27]
	s_cbranch_vccz .LBB0_858
	s_barrier
